# MIXC prompt path: 3 dummy loads warm next 16-row batch
# baseline (speedup 1.0000x reference)
; __device__ __forceinline__ float bf2f(bf16_t b) { return __uint_as_float(((unsigned)b) << 16); }
; __device__ __forceinline__ unsigned f2bf(float f) { return pk2(f, f) & 0xffffu; }
; __device__ __forceinline__ void mix_c_phase(Frame& F, int l, int rep) {
;     ...
;             const int r1 = (32 * hh + 32 < nvalid) ? 32 * hh + 32 : nvalid;
;             for (int r = 32 * hh; r < r1; ++r) {
;                 const size_t row = row0 + r;
;                 const float y = (bf2f(YAB[row * D + 512 + c]) + bf2f(PCG[row * 512 + c]) * carry) * bf2f(GGp[row * 512 + c]);
;                 if (rep) ((bf16_t*)(F.ws + WS_U))[row * 512 + c] = (bf16_t)f2bf(y); else
;                 YAB[row * D + 512 + c] = (bf16_t)f2bf(y);
.LBB0_42:
	v_lshlrev_b32_e32 v7, 1, v170
	v_and_b32_e32 v59, 15, v170
	v_and_b32_e32 v58, 0x3c0, v170
	v_lshlrev_b32_e32 v58, 1, v58
	v_lshl_add_u32 v57, v59, 11, v58
	v_lshl_add_u32 v58, v59, 10, v58
.Lmixc_pb:
	s_add_i32 s8, s88, s3
	s_lshl_b32 s38, s8, 11
	s_add_u32 s10, s74, s38
	s_addc_u32 s11, s75, 0
	s_add_u32 s10, s10, 0xc641400
	s_addc_u32 s11, s11, 0
	s_add_u32 s12, s10, 0x2000
	s_addc_u32 s13, s11, 0
	s_add_u32 s14, s12, 0x2000
	s_addc_u32 s15, s13, 0
	s_add_u32 s16, s14, 0x2000
	s_addc_u32 s17, s15, 0
	s_lshl_b32 s38, s8, 10
	s_add_u32 s18, s78, s38
	s_addc_u32 s19, s79, 0
	s_add_u32 s18, s18, 0x1000
	s_addc_u32 s19, s19, 0
	s_add_u32 s20, s18, 0x2000
	s_addc_u32 s21, s19, 0
	s_add_u32 s22, s80, s38
	s_addc_u32 s23, s81, 0
	s_add_u32 s22, s22, 0x1000
	s_addc_u32 s23, s23, 0
	s_add_u32 s24, s22, 0x2000
	s_addc_u32 s25, s23, 0
	s_add_u32 s26, s10, 0x7000
	s_addc_u32 s27, s11, 0
	global_load_dword v56, v57, s[26:27]
	s_add_u32 s26, s18, 0x3000
	s_addc_u32 s27, s19, 0
	global_load_dword v56, v58, s[26:27]
	s_add_u32 s26, s22, 0x3000
	s_addc_u32 s27, s23, 0
	global_load_dword v56, v58, s[26:27]
	global_load_ushort v8, v7, s[10:11] offset:-4096
	global_load_ushort v24, v7, s[18:19] offset:-4096
	global_load_ushort v40, v7, s[22:23] offset:-4096
	global_load_ushort v9, v7, s[10:11] offset:-2048
	global_load_ushort v25, v7, s[18:19] offset:-3072
	global_load_ushort v41, v7, s[22:23] offset:-3072
	global_load_ushort v10, v7, s[10:11]
	global_load_ushort v26, v7, s[18:19] offset:-2048
	global_load_ushort v42, v7, s[22:23] offset:-2048
	global_load_ushort v11, v7, s[10:11] offset:2048
	global_load_ushort v27, v7, s[18:19] offset:-1024
	global_load_ushort v43, v7, s[22:23] offset:-1024
	global_load_ushort v12, v7, s[12:13] offset:-4096
	global_load_ushort v28, v7, s[18:19]
	global_load_ushort v44, v7, s[22:23]
	global_load_ushort v13, v7, s[12:13] offset:-2048
	global_load_ushort v29, v7, s[18:19] offset:1024
	global_load_ushort v45, v7, s[22:23] offset:1024
	global_load_ushort v14, v7, s[12:13]
	global_load_ushort v30, v7, s[18:19] offset:2048
	global_load_ushort v46, v7, s[22:23] offset:2048
	global_load_ushort v15, v7, s[12:13] offset:2048
	global_load_ushort v31, v7, s[18:19] offset:3072
	global_load_ushort v47, v7, s[22:23] offset:3072
	global_load_ushort v16, v7, s[14:15] offset:-4096
	global_load_ushort v32, v7, s[20:21] offset:-4096
	global_load_ushort v48, v7, s[24:25] offset:-4096
	global_load_ushort v17, v7, s[14:15] offset:-2048
	global_load_ushort v33, v7, s[20:21] offset:-3072
	global_load_ushort v49, v7, s[24:25] offset:-3072
	global_load_ushort v18, v7, s[14:15]
	global_load_ushort v34, v7, s[20:21] offset:-2048
	global_load_ushort v50, v7, s[24:25] offset:-2048
	global_load_ushort v19, v7, s[14:15] offset:2048
	global_load_ushort v35, v7, s[20:21] offset:-1024
	global_load_ushort v51, v7, s[24:25] offset:-1024
	global_load_ushort v20, v7, s[16:17] offset:-4096
	global_load_ushort v36, v7, s[20:21]
	global_load_ushort v52, v7, s[24:25]
	global_load_ushort v21, v7, s[16:17] offset:-2048
	global_load_ushort v37, v7, s[20:21] offset:1024
	global_load_ushort v53, v7, s[24:25] offset:1024
	global_load_ushort v22, v7, s[16:17]
	global_load_ushort v38, v7, s[20:21] offset:2048
	global_load_ushort v54, v7, s[24:25] offset:2048
	global_load_ushort v23, v7, s[16:17] offset:2048
	global_load_ushort v39, v7, s[20:21] offset:3072
	global_load_ushort v55, v7, s[24:25] offset:3072
	s_waitcnt vmcnt(36)
	v_lshlrev_b32_e32 v8, 16, v8
	v_lshlrev_b32_e32 v24, 16, v24
	v_fmac_f32_e32 v8, v6, v24
	v_lshlrev_b32_e32 v40, 16, v40
	v_mul_f32_e32 v8, v8, v40
	v_cvt_pk_bf16_f32 v8, v8, v8
	global_store_short v7, v8, s[10:11] offset:-4096
	v_lshlrev_b32_e32 v9, 16, v9
	v_lshlrev_b32_e32 v25, 16, v25
	v_fmac_f32_e32 v9, v6, v25
	v_lshlrev_b32_e32 v41, 16, v41
	v_mul_f32_e32 v9, v9, v41
	v_cvt_pk_bf16_f32 v9, v9, v9
	global_store_short v7, v9, s[10:11] offset:-2048
	v_lshlrev_b32_e32 v10, 16, v10
	v_lshlrev_b32_e32 v26, 16, v26
	v_fmac_f32_e32 v10, v6, v26
	v_lshlrev_b32_e32 v42, 16, v42
	v_mul_f32_e32 v10, v10, v42
	v_cvt_pk_bf16_f32 v10, v10, v10
	global_store_short v7, v10, s[10:11]
	v_lshlrev_b32_e32 v11, 16, v11
	v_lshlrev_b32_e32 v27, 16, v27
	v_fmac_f32_e32 v11, v6, v27
	v_lshlrev_b32_e32 v43, 16, v43
	v_mul_f32_e32 v11, v11, v43
	v_cvt_pk_bf16_f32 v11, v11, v11
	global_store_short v7, v11, s[10:11] offset:2048
	s_waitcnt vmcnt(28)
; __device__ __forceinline__ float bf2f(bf16_t b) { return __uint_as_float(((unsigned)b) << 16); }
; __device__ __forceinline__ unsigned f2bf(float f) { return pk2(f, f) & 0xffffu; }
; __device__ __forceinline__ void mix_c_phase(Frame& F, int l, int rep) {
;     ...
;             for (int r = 32 * hh; r < r1; ++r) {
;                 const size_t row = row0 + r;
;                 const float y = (bf2f(YAB[row * D + 512 + c]) + bf2f(PCG[row * 512 + c]) * carry) * bf2f(GGp[row * 512 + c]);
;                 if (rep) ((bf16_t*)(F.ws + WS_U))[row * 512 + c] = (bf16_t)f2bf(y); else
;                 YAB[row * D + 512 + c] = (bf16_t)f2bf(y);
;             }
;             if (k == NCH_P - 1 && hh == 0) { const f32x2 ph = SUMM[(size_t)q * 512 + c]; F.out[O_HP + ((size_t)l * NB_P + b) * DB + c] = ph.y + ph.x * carry; }
	v_lshlrev_b32_e32 v12, 16, v12
	v_lshlrev_b32_e32 v28, 16, v28
	v_fmac_f32_e32 v12, v6, v28
	v_lshlrev_b32_e32 v44, 16, v44
	v_mul_f32_e32 v12, v12, v44
	v_cvt_pk_bf16_f32 v12, v12, v12
	global_store_short v7, v12, s[12:13] offset:-4096
	v_lshlrev_b32_e32 v13, 16, v13
	v_lshlrev_b32_e32 v29, 16, v29
	v_fmac_f32_e32 v13, v6, v29
	v_lshlrev_b32_e32 v45, 16, v45
	v_mul_f32_e32 v13, v13, v45
	v_cvt_pk_bf16_f32 v13, v13, v13
	global_store_short v7, v13, s[12:13] offset:-2048
	v_lshlrev_b32_e32 v14, 16, v14
	v_lshlrev_b32_e32 v30, 16, v30
	v_fmac_f32_e32 v14, v6, v30
	v_lshlrev_b32_e32 v46, 16, v46
	v_mul_f32_e32 v14, v14, v46
	v_cvt_pk_bf16_f32 v14, v14, v14
	global_store_short v7, v14, s[12:13]
	v_lshlrev_b32_e32 v15, 16, v15
	v_lshlrev_b32_e32 v31, 16, v31
	v_fmac_f32_e32 v15, v6, v31
	v_lshlrev_b32_e32 v47, 16, v47
	v_mul_f32_e32 v15, v15, v47
	v_cvt_pk_bf16_f32 v15, v15, v15
	global_store_short v7, v15, s[12:13] offset:2048
	s_waitcnt vmcnt(20)
	v_lshlrev_b32_e32 v16, 16, v16
	v_lshlrev_b32_e32 v32, 16, v32
	v_fmac_f32_e32 v16, v6, v32
	v_lshlrev_b32_e32 v48, 16, v48
	v_mul_f32_e32 v16, v16, v48
	v_cvt_pk_bf16_f32 v16, v16, v16
	global_store_short v7, v16, s[14:15] offset:-4096
	v_lshlrev_b32_e32 v17, 16, v17
	v_lshlrev_b32_e32 v33, 16, v33
	v_fmac_f32_e32 v17, v6, v33
	v_lshlrev_b32_e32 v49, 16, v49
	v_mul_f32_e32 v17, v17, v49
	v_cvt_pk_bf16_f32 v17, v17, v17
	global_store_short v7, v17, s[14:15] offset:-2048
	v_lshlrev_b32_e32 v18, 16, v18
	v_lshlrev_b32_e32 v34, 16, v34
	v_fmac_f32_e32 v18, v6, v34
	v_lshlrev_b32_e32 v50, 16, v50
	v_mul_f32_e32 v18, v18, v50
	v_cvt_pk_bf16_f32 v18, v18, v18
	global_store_short v7, v18, s[14:15]
	v_lshlrev_b32_e32 v19, 16, v19
	v_lshlrev_b32_e32 v35, 16, v35
	v_fmac_f32_e32 v19, v6, v35
	v_lshlrev_b32_e32 v51, 16, v51
	v_mul_f32_e32 v19, v19, v51
	v_cvt_pk_bf16_f32 v19, v19, v19
	global_store_short v7, v19, s[14:15] offset:2048
	s_waitcnt vmcnt(12)
	v_lshlrev_b32_e32 v20, 16, v20
	v_lshlrev_b32_e32 v36, 16, v36
	v_fmac_f32_e32 v20, v6, v36
	v_lshlrev_b32_e32 v52, 16, v52
	v_mul_f32_e32 v20, v20, v52
	v_cvt_pk_bf16_f32 v20, v20, v20
	global_store_short v7, v20, s[16:17] offset:-4096
	v_lshlrev_b32_e32 v21, 16, v21
	v_lshlrev_b32_e32 v37, 16, v37
	v_fmac_f32_e32 v21, v6, v37
	v_lshlrev_b32_e32 v53, 16, v53
	v_mul_f32_e32 v21, v21, v53
	v_cvt_pk_bf16_f32 v21, v21, v21
	global_store_short v7, v21, s[16:17] offset:-2048
	v_lshlrev_b32_e32 v22, 16, v22
	v_lshlrev_b32_e32 v38, 16, v38
	v_fmac_f32_e32 v22, v6, v38
	v_lshlrev_b32_e32 v54, 16, v54
	v_mul_f32_e32 v22, v22, v54
	v_cvt_pk_bf16_f32 v22, v22, v22
	global_store_short v7, v22, s[16:17]
	v_lshlrev_b32_e32 v23, 16, v23
	v_lshlrev_b32_e32 v39, 16, v39
	v_fmac_f32_e32 v23, v6, v39
	v_lshlrev_b32_e32 v55, 16, v55
	v_mul_f32_e32 v23, v23, v55
	v_cvt_pk_bf16_f32 v23, v23, v23
	global_store_short v7, v23, s[16:17] offset:2048
	s_add_i32 s3, s3, 16
	s_cmp_ge_u32 s3, s6
	s_cbranch_scc0 .Lmixc_pb
	s_cmp_eq_u32 s87, 0
	s_cselect_b64 s[6:7], -1, 0
	s_and_b64 s[6:7], s[6:7], s[70:71]
	s_and_b64 vcc, exec, s[6:7]
	s_cbranch_vccz .LBB0_31
	s_ashr_i32 s87, s86, 31
	s_lshl_b64 s[6:7], s[86:87], 12
	v_lshl_add_u64 v[8:9], v[2:3], 0, s[6:7]
	global_load_dwordx2 v[8:9], v[8:9], off
	s_ashr_i32 s3, s2, 31
	s_lshl_b64 s[2:3], s[2:3], 11
	v_readlane_b32 s6, v255, 18
	s_add_u32 s2, s6, s2
	v_readlane_b32 s6, v255, 19
	s_addc_u32 s3, s6, s3
	s_waitcnt vmcnt(0)
	v_fmac_f32_e32 v9, v6, v8
	v_lshl_add_u64 v[6:7], v[170:171], 2, s[2:3]
	v_add_co_u32_e32 v6, vcc, 0x4508000, v6
	s_nop 1
	v_addc_co_u32_e32 v7, vcc, 0, v7, vcc
	global_store_dword v[6:7], v9, off
	s_branch .LBB0_31
